# on top of previous: barrier arrive atomic (global_atomic_add, vmcnt only) issued before the two LDS state reads instead of after them
# speedup vs baseline: 1.0136x; 1.0051x over previous
; __device__ __forceinline__ int opq_tid() { int t = threadIdx.x; asm volatile("" : "+v"(t)); return t; }
; __device__ __forceinline__ unsigned xb_add(unsigned* p, unsigned v) { return __hip_atomic_fetch_add(p, v, __ATOMIC_RELAXED, __HIP_MEMORY_SCOPE_AGENT); }
; __device__ __forceinline__ void xcd_barrier(const XcdBarrier& b) {
;     asm volatile("s_waitcnt vmcnt(0)" ::: "memory");
;     __syncthreads();
;     if (opq_tid() == 0) {
;         unsigned* bar = b.bar;
;         __builtin_amdgcn_s_waitcnt(0);
;         unsigned nloc = b.st[0], nx = b.st[1];
;         if (nloc == 0u) { xcd_barrier_complete(bar, b.x, nloc, nx); b.st[0] = nloc; b.st[1] = nx; }
;         const unsigned old = xb_add(&bar[XB_XSUB(b.x)], 1u);
;         const unsigned gen = old / nloc;
.LBB0_800:
	s_and_b32 s38, s2, 15
	s_lshl_b32 s4, s38, 8
	s_add_u32 s4, s36, s4
	s_addc_u32 s5, s37, 0
	s_add_u32 s4, s4, 0x1000
	s_addc_u32 s5, s5, 0
	v_mov_b32_e32 v22, s4
	v_mov_b32_e32 v23, s5
	s_waitcnt vmcnt(0) expcnt(0) lgkmcnt(0)
	global_atomic_add v24, v[22:23], v243, off offset:1024 sc0
	v_mov_b32_e32 v1, s85
	s_waitcnt lgkmcnt(0)
	ds_read_b32 v4, v1
	v_readlane_b32 s3, v254, 24
	s_and_b32 s38, s2, 15
	s_waitcnt lgkmcnt(0)
	v_cmp_ne_u32_e32 vcc, 0, v4
	v_mov_b32_e32 v1, s3
	ds_read_b32 v2, v1
	s_cbranch_vccnz .LBB0_814
	s_add_u32 s2, s36, 0x1000
	s_addc_u32 s3, s37, 0
	s_add_u32 s4, s36, 0x1100
	s_addc_u32 s5, s37, 0
	s_add_u32 s6, s36, 0x1200
	s_addc_u32 s7, s37, 0
	s_add_u32 s8, s36, 0x1300
	s_addc_u32 s9, s37, 0
	s_mov_b32 s28, 1
	s_mov_b64 s[10:11], 0
	s_branch .LBB0_804

; __device__ __forceinline__ unsigned xb_ld(unsigned* p)              { return __hip_atomic_load(p, __ATOMIC_RELAXED, __HIP_MEMORY_SCOPE_AGENT); }
; __device__ __forceinline__ unsigned xb_add(unsigned* p, unsigned v) { return __hip_atomic_fetch_add(p, v, __ATOMIC_RELAXED, __HIP_MEMORY_SCOPE_AGENT); }
; #define XB_SPIN(cond, bar) do { unsigned _sp = 0; while (cond) { __builtin_amdgcn_s_sleep(1); \
;     if ((++_sp & 255u) == 0u) { if (xb_ld(&(bar)[XB_TMO])) break; if (_sp > XB_SPIN_CAP) { atomicAdd(&(bar)[XB_TMO], 1u); break; } } } } while (0)
; __device__ __forceinline__ void xcd_barrier(const XcdBarrier& b) {
;     ...
;         unsigned nloc = b.st[0], nx = b.st[1];
;         if (nloc == 0u) { xcd_barrier_complete(bar, b.x, nloc, nx); b.st[0] = nloc; b.st[1] = nx; }
;         const unsigned old = xb_add(&bar[XB_XSUB(b.x)], 1u);
;         const unsigned gen = old / nloc;
;         if (old + 1u == (gen + 1u) * nloc) {
;             __builtin_amdgcn_fence(__ATOMIC_RELEASE, "agent");
;             asm volatile("s_waitcnt vmcnt(0)" ::: "memory");
;             const unsigned og = xb_add(&bar[XB_TOP], 1u);
;             const unsigned tg = og / nx;
;             if (og + 1u == (tg + 1u) * nx) xb_add(&bar[XB_TOPGEN], 1u);
;             else XB_SPIN(xb_ld(&bar[XB_TOPGEN]) == tg, bar);
.LBB0_814:
	s_lshl_b32 s2, s38, 8
	s_add_u32 s23, s36, s2
	s_addc_u32 s22, s37, 0
	v_cvt_f32_u32_e32 v1, v4
	v_sub_u32_e32 v5, 0, v4
	v_rcp_iflag_f32_e32 v1, v1
	s_nop 0
	v_mul_f32_e32 v1, 0x4f7ffffe, v1
	v_cvt_u32_f32_e32 v1, v1
	v_mul_lo_u32 v5, v5, v1
	v_mul_hi_u32 v5, v1, v5
	v_add_u32_e32 v1, v1, v5
	s_waitcnt vmcnt(0) lgkmcnt(0)
	v_mov_b32_e32 v3, v24
	v_mul_hi_u32 v1, v3, v1
	v_mul_lo_u32 v5, v1, v4
	v_sub_u32_e32 v5, v3, v5
	v_cmp_ge_u32_e32 vcc, v5, v4
	v_add_u32_e32 v6, 1, v1
	v_add_u32_e32 v3, 1, v3
	v_cndmask_b32_e32 v1, v1, v6, vcc
	v_sub_u32_e32 v6, v5, v4
	v_cndmask_b32_e32 v5, v5, v6, vcc
	v_cmp_ge_u32_e32 vcc, v5, v4
	v_add_u32_e32 v5, 1, v1
	s_nop 0
	v_cndmask_b32_e32 v1, v1, v5, vcc
	v_mad_u64_u32 v[4:5], s[2:3], v4, v1, v[4:5]
	v_cmp_ne_u32_e32 vcc, v3, v4
	s_and_saveexec_b64 s[2:3], vcc
	s_xor_b64 s[2:3], exec, s[2:3]
	s_cbranch_execz .LBB0_827
	v_mov_b32_e32 v2, s23
	v_add_co_u32_e32 v2, vcc, 0x2000, v2
	v_mov_b32_e32 v3, s22
	s_nop 0
	v_addc_co_u32_e32 v3, vcc, 0, v3, vcc
	flat_load_dword v2, v[2:3] offset:1024 sc1
	s_add_u32 s6, s23, 0x2400
	s_addc_u32 s7, s22, 0
	s_waitcnt vmcnt(0) lgkmcnt(0)
	v_cmp_eq_u32_e32 vcc, v2, v1
	s_and_saveexec_b64 s[4:5], vcc
	s_cbranch_execz .LBB0_826
	s_mov_b32 s24, 1
	s_mov_b64 s[8:9], 0
	s_branch .LBB0_818
